# neighbourhood-attention loop: one barrier per key tile (V staging write deferred past the barrier via spare registers)
# baseline (speedup 1.0000x reference)
; __device__ __forceinline__ void partialSM(f32x16& p0, f32x16& p1, float& m_reg, float& mn, float& alpha, float C, float thrRaw) {
;   float pmax = p0[0];
; #pragma unroll
;   for (int r = 1; r < 16; ++r) pmax = fmaxf(pmax, p0[r]);
; #pragma unroll
;   for (int r = 0; r < 16; ++r) pmax = fmaxf(pmax, p1[r]);
;   { auto rr = __builtin_amdgcn_permlane32_swap(__float_as_uint(pmax), __float_as_uint(pmax), false, false);
;     pmax = fmaxf(__uint_as_float(rr[0]), __uint_as_float(rr[1])); }
;   if (__builtin_expect(__all(pmax - m_reg <= thrRaw), 1)) { mn = m_reg; alpha = 1.f; }
;   else { mn = fmaxf(m_reg, pmax); alpha = __builtin_amdgcn_exp2f((m_reg - mn) * C); m_reg = mn; }
;   float mnC = -mn * C;
; #pragma unroll
;   for (int r = 0; r < 16; ++r) p0[r] = fmaf(p0[r], C, mnC);
; #pragma unroll
;   for (int r = 0; r < 16; ++r) p1[r] = fmaf(p1[r], C, mnC);
; #pragma unroll
;   for (int r = 0; r < 16; ++r) p0[r] = __builtin_amdgcn_exp2f(p0[r]);
; }
; __device__ __forceinline__ void finishSM(f32x16& p0, f32x16& p1, float alpha, float& l_reg, bf16x8& pa0, bf16x8& pa1, bf16x8& pa2, bf16x8& pa3) {
; #pragma unroll
;   for (int r = 0; r < 16; ++r) p1[r] = __builtin_amdgcn_exp2f(p1[r]);
;   float ps = 0;
; #pragma unroll
;   for (int r = 0; r < 16; ++r) ps += p0[r];
; #pragma unroll
;   for (int r = 0; r < 16; ++r) ps += p1[r];
;   { auto rr = __builtin_amdgcn_permlane32_swap(__float_as_uint(ps), __float_as_uint(ps), false, false);
;     ps = __uint_as_float(rr[0]) + __uint_as_float(rr[1]); }
;   l_reg = l_reg * alpha + ps;
;     ...
;   PK4(p0, 0, pa0); PK4(p0, 8, pa1); PK4(p1, 0, pa2); PK4(p1, 8, pa3);
;     ...
; }
; template <int D0> __device__ __forceinline__ void pv_one(f32x16& od, int vb, bf16x8 pa0, bf16x8 pa1, bf16x8 pa2, bf16x8 pa3) {
;   const s16x4 l0 = tr_read<v_rd_off(D0, 0, 0)>(vb), h0 = tr_read<v_rd_off(D0, 0, 1)>(vb), l1 = tr_read<v_rd_off(D0, 1, 0)>(vb), h1 = tr_read<v_rd_off(D0, 1, 1)>(vb);
;   const s16x4 l2 = tr_read<v_rd_off(D0, 2, 0)>(vb), h2 = tr_read<v_rd_off(D0, 2, 1)>(vb), l3 = tr_read<v_rd_off(D0, 3, 0)>(vb), h3 = tr_read<v_rd_off(D0, 3, 1)>(vb);
;   asm volatile("s_waitcnt lgkmcnt(0)" ::: "memory"); SBAR();
;     ...
;   od = __builtin_amdgcn_mfma_f32_32x32x16_bf16(pa0, PK(l0, h0), od, 0, 0, 0);
;   od = __builtin_amdgcn_mfma_f32_32x32x16_bf16(pa1, PK(l1, h1), od, 0, 0, 0);
;   od = __builtin_amdgcn_mfma_f32_32x32x16_bf16(pa2, PK(l2, h2), od, 0, 0, 0);
.LBB0_513:
	s_or_b64 exec, exec, s[36:37]
	v_add_f32_e32 v2, 0, v94
	v_add_f32_e32 v2, v95, v2
	v_add_f32_e32 v2, v92, v2
	v_add_f32_e32 v2, v93, v2
	v_add_f32_e32 v2, v88, v2
	v_add_f32_e32 v2, v89, v2
	v_add_f32_e32 v2, v90, v2
	v_add_f32_e32 v2, v91, v2
	v_add_f32_e32 v2, v80, v2
	v_add_f32_e32 v2, v81, v2
	v_add_f32_e32 v2, v82, v2
	v_add_f32_e32 v2, v83, v2
	v_exp_f32_e32 v111, v144
	v_add_f32_e32 v2, v84, v2
	v_exp_f32_e32 v114, v145
	v_add_f32_e32 v2, v85, v2
	v_exp_f32_e32 v116, v142
	v_add_f32_e32 v2, v86, v2
	v_exp_f32_e32 v127, v143
	v_add_f32_e32 v2, v87, v2
	v_exp_f32_e32 v140, v140
	v_add_f32_e32 v2, v111, v2
	v_exp_f32_e32 v141, v141
	v_add_f32_e32 v2, v114, v2
	v_exp_f32_e32 v138, v138
	v_add_f32_e32 v2, v116, v2
	v_exp_f32_e32 v139, v139
	v_add_f32_e32 v2, v127, v2
	v_exp_f32_e32 v6, v136
	v_add_f32_e32 v2, v140, v2
	v_exp_f32_e32 v7, v137
	v_add_f32_e32 v2, v141, v2
	v_exp_f32_e32 v8, v134
	v_add_f32_e32 v2, v138, v2
	v_exp_f32_e32 v9, v135
	v_add_f32_e32 v2, v139, v2
	v_exp_f32_e32 v10, v132
	v_add_f32_e32 v2, v6, v2
	v_exp_f32_e32 v11, v133
	v_add_f32_e32 v2, v7, v2
	v_exp_f32_e32 v12, v130
	v_add_f32_e32 v2, v8, v2
	v_exp_f32_e32 v13, v131
	v_add_f32_e32 v2, v9, v2
	v_add_f32_e32 v2, v10, v2
	v_add_f32_e32 v2, v11, v2
	v_add_f32_e32 v2, v12, v2
	v_add_f32_e32 v112, v13, v2
	v_mov_b32_e32 v113, v112
	v_cvt_pk_bf16_f32 v2, v94, v95
	v_cvt_pk_bf16_f32 v3, v92, v93
	v_cvt_pk_bf16_f32 v4, v88, v89
	s_nop 1
	v_permlane32_swap_b32_e32 v112, v113
	v_cvt_pk_bf16_f32 v5, v90, v91
	v_permlane32_swap_b32_e32 v2, v4
	v_cvt_pk_bf16_f32 v88, v80, v81
	v_cvt_pk_bf16_f32 v89, v82, v83
	v_cvt_pk_bf16_f32 v90, v84, v85
	v_cvt_pk_bf16_f32 v91, v86, v87
	v_cvt_pk_bf16_f32 v92, v111, v114
	v_cvt_pk_bf16_f32 v93, v116, v127
	v_cvt_pk_bf16_f32 v94, v140, v141
	v_cvt_pk_bf16_f32 v95, v138, v139
	v_cvt_pk_bf16_f32 v130, v6, v7
	v_cvt_pk_bf16_f32 v131, v8, v9
	v_cvt_pk_bf16_f32 v132, v10, v11
	v_cvt_pk_bf16_f32 v133, v12, v13
	v_permlane32_swap_b32_e32 v3, v5
	v_permlane32_swap_b32_e32 v88, v90
	v_permlane32_swap_b32_e32 v89, v91
	v_permlane32_swap_b32_e32 v92, v94
	v_permlane32_swap_b32_e32 v93, v95
	v_permlane32_swap_b32_e32 v130, v132
	v_permlane32_swap_b32_e32 v131, v133
	s_mov_b32 s36, 0x50000
	v_add_co_u32_e32 v80, vcc, s36, v128
	s_nop 1
	v_addc_co_u32_e32 v81, vcc, 0, v129, vcc
	global_load_dwordx4 v[6:9], v[128:129], off offset:1024
	global_load_dwordx4 v[10:13], v[128:129], off
	global_load_dwordx4 v[84:87], v[80:81], off offset:1024
	s_nop 0
	global_load_dwordx4 v[80:83], v[80:81], off
	ds_read_b64_tr_b16 v[134:135], v151 offset:0
	ds_read_b64_tr_b16 v[136:137], v151 offset:0x800
	ds_read_b64_tr_b16 v[138:139], v151 offset:0x1000
	ds_read_b64_tr_b16 v[140:141], v151 offset:0x1800
	ds_read_b64_tr_b16 v[142:143], v151 offset:0x2000
	ds_read_b64_tr_b16 v[144:145], v151 offset:0x2800
	ds_read_b64_tr_b16 v[246:247], v151 offset:0x3000
	ds_read_b64_tr_b16 v[248:249], v151 offset:0x3800
	s_waitcnt lgkmcnt(0)
	s_nop 0
	v_mfma_f32_32x32x16_bf16 v[32:47], v[2:5], v[134:137], v[32:47]
	ds_read_b64_tr_b16 v[134:135], v151 offset:0x200
	ds_read_b64_tr_b16 v[136:137], v151 offset:0xa00
	v_mfma_f32_32x32x16_bf16 v[32:47], v[88:91], v[138:141], v[32:47]
	ds_read_b64_tr_b16 v[138:139], v151 offset:0x1200
	ds_read_b64_tr_b16 v[140:141], v151 offset:0x1a00
	v_mfma_f32_32x32x16_bf16 v[32:47], v[92:95], v[142:145], v[32:47]
	ds_read_b64_tr_b16 v[142:143], v151 offset:0x2200
	ds_read_b64_tr_b16 v[144:145], v151 offset:0x2a00
	v_mfma_f32_32x32x16_bf16 v[32:47], v[130:133], v[246:249], v[32:47]
	ds_read_b64_tr_b16 v[246:247], v151 offset:0x3200
	ds_read_b64_tr_b16 v[248:249], v151 offset:0x3a00
	s_waitcnt lgkmcnt(0)
	v_mfma_f32_32x32x16_bf16 v[64:79], v[2:5], v[134:137], v[64:79]
	ds_read_b64_tr_b16 v[134:135], v151 offset:0x400
	ds_read_b64_tr_b16 v[136:137], v151 offset:0xc00
	v_mfma_f32_32x32x16_bf16 v[64:79], v[88:91], v[138:141], v[64:79]
	ds_read_b64_tr_b16 v[138:139], v151 offset:0x1400
	ds_read_b64_tr_b16 v[140:141], v151 offset:0x1c00
	v_mfma_f32_32x32x16_bf16 v[64:79], v[92:95], v[142:145], v[64:79]
	ds_read_b64_tr_b16 v[142:143], v151 offset:0x2400
	ds_read_b64_tr_b16 v[144:145], v151 offset:0x2c00
	v_mfma_f32_32x32x16_bf16 v[64:79], v[130:133], v[246:249], v[64:79]
	ds_read_b64_tr_b16 v[246:247], v151 offset:0x3400
	ds_read_b64_tr_b16 v[248:249], v151 offset:0x3c00
	s_waitcnt lgkmcnt(0)
	v_mfma_f32_32x32x16_bf16 v[16:31], v[2:5], v[134:137], v[16:31]
	ds_read_b64_tr_b16 v[134:135], v151 offset:0x600
	ds_read_b64_tr_b16 v[136:137], v151 offset:0xe00
	v_mfma_f32_32x32x16_bf16 v[16:31], v[88:91], v[138:141], v[16:31]
	ds_read_b64_tr_b16 v[138:139], v151 offset:0x1600
	ds_read_b64_tr_b16 v[140:141], v151 offset:0x1e00
	v_mfma_f32_32x32x16_bf16 v[16:31], v[92:95], v[142:145], v[16:31]
	ds_read_b64_tr_b16 v[142:143], v151 offset:0x2600
	ds_read_b64_tr_b16 v[144:145], v151 offset:0x2e00
	v_mfma_f32_32x32x16_bf16 v[16:31], v[130:133], v[246:249], v[16:31]
	ds_read_b64_tr_b16 v[246:247], v151 offset:0x3600
	ds_read_b64_tr_b16 v[248:249], v151 offset:0x3e00
	s_waitcnt lgkmcnt(0)
	v_mfma_f32_32x32x16_bf16 v[48:63], v[2:5], v[134:137], v[48:63]
	v_max_f32_e32 v2, v96, v96
	v_max_f32_e32 v3, v14, v14
	v_max_f32_e32 v2, v3, v2
	v_max3_f32 v2, v2, v243, v244
	v_max3_f32 v2, v2, v115, v245
	v_max3_f32 v2, v2, v117, v118
	v_max3_f32 v2, v2, v119, v120
	v_max3_f32 v2, v2, v121, v122
	v_max3_f32 v2, v2, v123, v124
	v_mfma_f32_32x32x16_bf16 v[48:63], v[88:91], v[138:141], v[48:63]
	v_max3_f32 v2, v2, v125, v126
	v_max3_f32 v2, v2, v0, v15
	v_max3_f32 v2, v2, v97, v98
	v_max3_f32 v2, v2, v99, v100
	v_max3_f32 v2, v2, v101, v102
	v_max3_f32 v2, v2, v103, v104
	v_max3_f32 v2, v2, v105, v106
	v_max3_f32 v2, v2, v107, v108
	v_mfma_f32_32x32x16_bf16 v[48:63], v[92:95], v[142:145], v[48:63]
	v_max3_f32 v2, v2, v109, v110
	v_mov_b32_e32 v3, v2
	s_nop 1
	v_permlane32_swap_b32_e32 v2, v3
	v_max_f32_e32 v3, v3, v3
	v_max_f32_e32 v2, v2, v2
	v_max_f32_e32 v2, v2, v3
	v_sub_f32_e32 v3, v2, v237
	s_mov_b32 s36, 0x42b504f3
	v_cmp_ge_f32_e32 vcc, s36, v3
	v_max_f32_e32 v3, v237, v237
	v_max_f32_e32 v2, v3, v2
	v_mfma_f32_32x32x16_bf16 v[48:63], v[130:133], v[246:249], v[48:63]
	v_sub_f32_e32 v3, v237, v2
	v_mul_f32_e32 v3, 0x3e0293ee, v3
	v_exp_f32_e32 v3, v3
	s_cmp_eq_u64 vcc, exec
	s_cselect_b64 s[36:37], -1, 0
	s_waitcnt vmcnt(0)
	v_cndmask_b32_e64 v114, v3, 1.0, s[36:37]
	v_cmp_gt_f32_e32 vcc, 1.0, v114
	v_mov_b64_e32 v[168:169], v[6:7]
	v_mov_b64_e32 v[170:171], v[8:9]
	v_mov_b64_e32 v[194:195], v[84:85]
	v_mov_b64_e32 v[196:197], v[86:87]
	ds_write_b128 v156, v[10:13] offset:32768
	ds_write_b128 v157, v[80:83] offset:32768
	s_cbranch_vccz .LBB0_517
	s_mov_b64 s[48:49], exec
	v_readlane_b32 s52, v255, 58
	v_readlane_b32 s53, v255, 59
	s_and_b64 s[52:53], s[48:49], s[52:53]
	s_mov_b64 exec, s[52:53]
	ds_write_b32 v148, v114 offset:128
	s_or_b64 exec, exec, s[48:49]
	s_waitcnt lgkmcnt(0)
	ds_read_b128 v[4:7], v146 offset:128
	ds_read_b128 v[8:11], v146 offset:160
	ds_read_b128 v[80:83], v146 offset:192
	ds_read_b128 v[84:87], v146 offset:224
	s_waitcnt lgkmcnt(3)
	v_pk_mul_f32 v[64:65], v[4:5], v[64:65]
	v_pk_mul_f32 v[66:67], v[66:67], v[6:7]
	s_waitcnt lgkmcnt(2)
	v_pk_mul_f32 v[68:69], v[68:69], v[8:9]
	v_pk_mul_f32 v[70:71], v[70:71], v[10:11]
	s_waitcnt lgkmcnt(1)
	v_pk_mul_f32 v[72:73], v[72:73], v[80:81]
	v_pk_mul_f32 v[74:75], v[74:75], v[82:83]
	s_waitcnt lgkmcnt(0)
	v_pk_mul_f32 v[76:77], v[76:77], v[84:85]
	v_pk_mul_f32 v[46:47], v[46:47], v[86:87]
	v_pk_mul_f32 v[42:43], v[42:43], v[82:83]
	v_pk_mul_f32 v[38:39], v[38:39], v[10:11]
	v_pk_mul_f32 v[34:35], v[34:35], v[6:7]
	v_pk_mul_f32 v[44:45], v[44:45], v[84:85]
	v_pk_mul_f32 v[40:41], v[40:41], v[80:81]
	v_pk_mul_f32 v[36:37], v[36:37], v[8:9]
	v_pk_mul_f32 v[32:33], v[32:33], v[4:5]
	v_pk_mul_f32 v[78:79], v[78:79], v[86:87]
	v_pk_mul_f32 v[48:49], v[4:5], v[48:49]
	v_pk_mul_f32 v[50:51], v[50:51], v[6:7]
	v_pk_mul_f32 v[52:53], v[52:53], v[8:9]
	v_pk_mul_f32 v[54:55], v[54:55], v[10:11]
	v_pk_mul_f32 v[56:57], v[56:57], v[80:81]
	v_pk_mul_f32 v[58:59], v[58:59], v[82:83]
	v_pk_mul_f32 v[60:61], v[60:61], v[84:85]
	v_pk_mul_f32 v[30:31], v[30:31], v[86:87]
	v_pk_mul_f32 v[26:27], v[26:27], v[82:83]
	v_pk_mul_f32 v[22:23], v[22:23], v[10:11]
	v_pk_mul_f32 v[18:19], v[18:19], v[6:7]
	v_pk_mul_f32 v[28:29], v[28:29], v[84:85]
	v_pk_mul_f32 v[24:25], v[24:25], v[80:81]
	v_pk_mul_f32 v[20:21], v[20:21], v[8:9]
	v_pk_mul_f32 v[16:17], v[16:17], v[4:5]
	v_pk_mul_f32 v[62:63], v[62:63], v[86:87]
; __device__ __forceinline__ int crow(int r, int hi) { return (r & 3) + 8 * (r >> 2) + 4 * hi; }
; __device__ __forceinline__ void partialSM(f32x16& p0, f32x16& p1, float& m_reg, float& mn, float& alpha, float C, float thrRaw) {
;     ...
;   float mnC = -mn * C;
; #pragma unroll
;   for (int r = 0; r < 16; ++r) p0[r] = fmaf(p0[r], C, mnC);
; #pragma unroll
;   for (int r = 0; r < 16; ++r) p1[r] = fmaf(p1[r], C, mnC);
; #pragma unroll
;   for (int r = 0; r < 16; ++r) p0[r] = __builtin_amdgcn_exp2f(p0[r]);
; template <int DK, bool QL>
; __device__ __forceinline__ void qkt(f32x16& p0, f32x16& p1, const bf16* Ks, const bf16x8* qr, const char* ql, int r32, int hi) {
;   p0 = f32x16{}; p1 = f32x16{};
; #pragma unroll
;   for (int d0 = 0; d0 < DK / 16; ++d0) { int cb = (d0 * 16 + hi * 8) * 2;
;     const bf16x8 qv = QL ? *reinterpret_cast<const bf16x8*>(ql + d0 * 1024) : qr[d0];
;     bf16x8 b0 = *reinterpret_cast<const bf16x8*>((const char*)Ks + kswz<DK>(r32, cb));
;     bf16x8 b1 = *reinterpret_cast<const bf16x8*>((const char*)Ks + kswz<DK>(32 + r32, cb));
;     p0 = __builtin_amdgcn_mfma_f32_32x32x16_bf16(b0, qv, p0, 0, 0, 0);
;     p1 = __builtin_amdgcn_mfma_f32_32x32x16_bf16(b1, qv, p1, 0, 0, 0); }
; }
; __device__ __forceinline__ void na_hook(f32x16& p0, f32x16& p1, int kr, int q_row, int q_col, int win_r, int win_c, const float* rpb, float inv_scale, int hi) {
;   const bool rowok = (kr >= win_r) && (kr < win_r + 8);
;   int ir = kr - q_row + 7; ir = ir < 0 ? 0 : (ir > 14 ? 14 : ir);
;   const float* rp = rpb + ir * 31;
; #pragma unroll
;   for (int r = 0; r < 16; ++r) {
;     const int kc = crow(r, hi);
;     { const bool ok = rowok && kc >= win_c && kc < win_c + 16; int ic = kc - q_col + 15; ic = ic < 0 ? 0 : (ic > 30 ? 30 : ic);
;       p0[r] = ok ? fmaf(rp[ic], inv_scale, p0[r]) : -1e30f; }
;     { const int kc2 = kc + 32; const bool ok = rowok && kc2 >= win_c && kc2 < win_c + 16; int ic = kc2 - q_col + 15; ic = ic < 0 ? 0 : (ic > 30 ? 30 : ic);
;       p1[r] = ok ? fmaf(rp[ic], inv_scale, p1[r]) : -1e30f; }
;   }
; }
.LBB0_517:
	v_cndmask_b32_e64 v116, v2, v237, s[36:37]
	v_mul_f32_e32 v127, 0xbe0293ee, v116
	v_fmamk_f32 v2, v14, 0x3e0293ee, v127
	v_fmamk_f32 v3, v96, 0x3e0293ee, v127
	v_fmamk_f32 v4, v243, 0x3e0293ee, v127
	v_fmamk_f32 v5, v244, 0x3e0293ee, v127
	v_fmamk_f32 v6, v115, 0x3e0293ee, v127
	v_fmamk_f32 v7, v245, 0x3e0293ee, v127
	v_fmamk_f32 v8, v117, 0x3e0293ee, v127
	v_fmamk_f32 v11, v118, 0x3e0293ee, v127
	v_fmamk_f32 v14, v119, 0x3e0293ee, v127
	v_fmamk_f32 v80, v120, 0x3e0293ee, v127
	v_fmamk_f32 v81, v121, 0x3e0293ee, v127
	v_fmamk_f32 v82, v122, 0x3e0293ee, v127
	v_fmamk_f32 v83, v123, 0x3e0293ee, v127
	v_fmamk_f32 v84, v124, 0x3e0293ee, v127
	v_fmamk_f32 v85, v125, 0x3e0293ee, v127
	v_fmamk_f32 v86, v126, 0x3e0293ee, v127
	v_fmamk_f32 v124, v0, 0x3e0293ee, v127
	v_exp_f32_e32 v121, v2
	v_exp_f32_e32 v123, v3
	v_exp_f32_e32 v12, v4
	v_exp_f32_e32 v122, v5
	v_exp_f32_e32 v10, v6
	v_exp_f32_e32 v13, v7
	v_exp_f32_e32 v9, v8
	v_exp_f32_e32 v11, v11
	v_exp_f32_e32 v6, v14
	v_exp_f32_e32 v8, v80
	v_exp_f32_e32 v4, v81
	v_exp_f32_e32 v7, v82
	v_exp_f32_e32 v2, v83
	v_exp_f32_e32 v5, v84
	v_exp_f32_e32 v0, v85
	v_exp_f32_e32 v3, v86
	v_fmamk_f32 v125, v15, 0x3e0293ee, v127
	v_fmamk_f32 v126, v97, 0x3e0293ee, v127
	v_fmamk_f32 v130, v98, 0x3e0293ee, v127
	v_fmamk_f32 v131, v99, 0x3e0293ee, v127
	v_fmamk_f32 v132, v100, 0x3e0293ee, v127
	v_fmamk_f32 v133, v101, 0x3e0293ee, v127
	v_fmamk_f32 v134, v102, 0x3e0293ee, v127
	v_fmamk_f32 v135, v103, 0x3e0293ee, v127
	v_fmamk_f32 v136, v104, 0x3e0293ee, v127
	v_fmamk_f32 v137, v105, 0x3e0293ee, v127
	v_fmamk_f32 v138, v106, 0x3e0293ee, v127
	v_fmamk_f32 v139, v107, 0x3e0293ee, v127
	v_fmamk_f32 v140, v108, 0x3e0293ee, v127
	v_fmamk_f32 v141, v109, 0x3e0293ee, v127
	v_fmac_f32_e32 v127, 0x3e0293ee, v110
	s_mov_b64 s[52:53], s[54:55]
	s_waitcnt lgkmcnt(0)
	s_barrier
	ds_write_b128 v152, v[168:171]
	ds_write_b128 v153, v[194:197]
	ds_read_b128 v[80:83], v147
	ds_read_b128 v[84:87], v158 offset:32768
	ds_read_b128 v[88:91], v158 offset:40960
	ds_read_b128 v[142:145], v147 offset:1024
	ds_read_b128 v[244:247], v159 offset:32768
	ds_read_b128 v[164:167], v159 offset:40960
	s_add_i32 s50, s50, -1
	v_readlane_b32 s36, v255, 32
	s_waitcnt lgkmcnt(4)
	v_mfma_f32_32x32x16_bf16 v[96:111], v[84:87], v[80:83], 0
	s_cmp_lt_u32 s50, s36
	v_readlane_b32 s48, v255, 33
	s_cselect_b64 s[36:37], -1, 0
	s_cmp_ge_u32 s50, s48
	s_cselect_b64 s[48:49], -1, 0
	s_add_i32 s51, s51, -1
	s_or_b64 s[36:37], s[36:37], s[48:49]
	s_waitcnt lgkmcnt(3)
	v_mfma_f32_32x32x16_bf16 v[80:95], v[88:91], v[80:83], 0
	v_med3_i32 v14, s51, -7, 7
	s_movk_i32 s48, 0x7c
	v_mul_lo_u32 v14, v14, s48
	v_readlane_b32 s48, v255, 50
	v_add_u32_e32 v14, 0, v14
	v_readlane_b32 s49, v255, 51
	s_nor_b64 s[50:51], s[48:49], s[36:37]
	s_waitcnt lgkmcnt(1)
	v_mfma_f32_32x32x16_bf16 v[96:111], v[244:247], v[142:145], v[96:111]
	v_mov_b32_e32 v115, 0xf149f2ca
	s_waitcnt lgkmcnt(0)
	v_mfma_f32_32x32x16_bf16 v[80:95], v[164:167], v[142:145], v[80:95]
	ds_read_b128 v[142:145], v147 offset:2048
	ds_read_b128 v[164:167], v160 offset:32768
	ds_read_b128 v[244:247], v160 offset:40960
	s_waitcnt lgkmcnt(1)
	v_mfma_f32_32x32x16_bf16 v[96:111], v[164:167], v[142:145], v[96:111]
	s_waitcnt lgkmcnt(0)
	v_mfma_f32_32x32x16_bf16 v[80:95], v[244:247], v[142:145], v[80:95]
	ds_read_b128 v[142:145], v147 offset:3072
	ds_read_b128 v[164:167], v161 offset:32768
	ds_read_b128 v[244:247], v161 offset:40960
	s_waitcnt lgkmcnt(1)
	v_mfma_f32_32x32x16_bf16 v[96:111], v[164:167], v[142:145], v[96:111]
	s_waitcnt lgkmcnt(0)
	v_mfma_f32_32x32x16_bf16 v[80:95], v[244:247], v[142:145], v[80:95]
	ds_read_b128 v[142:145], v147 offset:4096
	ds_read_b128 v[164:167], v176 offset:32768
	ds_read_b128 v[244:247], v176 offset:40960
	s_waitcnt lgkmcnt(1)
	v_mfma_f32_32x32x16_bf16 v[96:111], v[164:167], v[142:145], v[96:111]
	s_waitcnt lgkmcnt(0)
	v_mfma_f32_32x32x16_bf16 v[80:95], v[244:247], v[142:145], v[80:95]
	ds_read_b128 v[142:145], v147 offset:5120
	ds_read_b128 v[164:167], v177 offset:32768
	ds_read_b128 v[244:247], v177 offset:40960
	s_waitcnt lgkmcnt(1)
	v_mfma_f32_32x32x16_bf16 v[96:111], v[164:167], v[142:145], v[96:111]
	s_waitcnt lgkmcnt(0)
	v_mfma_f32_32x32x16_bf16 v[80:95], v[244:247], v[142:145], v[80:95]
	ds_read_b128 v[142:145], v147 offset:6144
	ds_read_b128 v[164:167], v207 offset:32768
	ds_read_b128 v[244:247], v207 offset:40960
	s_waitcnt lgkmcnt(1)
	v_mfma_f32_32x32x16_bf16 v[96:111], v[164:167], v[142:145], v[96:111]
	s_waitcnt lgkmcnt(0)
	v_mfma_f32_32x32x16_bf16 v[80:95], v[244:247], v[142:145], v[80:95]
	ds_read_b128 v[142:145], v147 offset:7168
	ds_read_b128 v[164:167], v208 offset:32768
	ds_read_b128 v[244:247], v208 offset:40960
	s_waitcnt lgkmcnt(1)
	v_mfma_f32_32x32x16_bf16 v[96:111], v[164:167], v[142:145], v[96:111]
	s_waitcnt lgkmcnt(0)
	v_mfma_f32_32x32x16_bf16 v[80:95], v[244:247], v[142:145], v[80:95]
	v_add_u32_e32 v142, 0x10800, v14
	v_mov_b32_e32 v14, 0xf149f2ca
	v_lshl_add_u32 v162, v242, 2, v142
	ds_read_b32 v162, v162 offset:928
	v_lshl_add_u32 v178, v209, 2, v142
	ds_read_b32 v178, v178 offset:928
	v_lshl_add_u32 v179, v210, 2, v142
	ds_read_b32 v179, v179 offset:928
	v_lshl_add_u32 v180, v211, 2, v142
	ds_read_b32 v180, v180 offset:928
	v_lshl_add_u32 v201, v212, 2, v142
	ds_read_b32 v201, v201 offset:928
	v_lshl_add_u32 v202, v213, 2, v142
	ds_read_b32 v202, v202 offset:928
	v_lshl_add_u32 v168, v214, 2, v142
	ds_read_b32 v168, v168 offset:928
	v_lshl_add_u32 v169, v215, 2, v142
	ds_read_b32 v169, v169 offset:928
	v_lshl_add_u32 v170, v216, 2, v142
	ds_read_b32 v170, v170 offset:928
	v_lshl_add_u32 v171, v217, 2, v142
	ds_read_b32 v171, v171 offset:928
	v_lshl_add_u32 v190, v218, 2, v142
	ds_read_b32 v190, v190 offset:928
	v_lshl_add_u32 v191, v219, 2, v142
	ds_read_b32 v191, v191 offset:928
	v_lshl_add_u32 v193, v220, 2, v142
	ds_read_b32 v193, v193 offset:928
	v_lshl_add_u32 v194, v221, 2, v142
	ds_read_b32 v194, v194 offset:928
	v_lshl_add_u32 v195, v222, 2, v142
	ds_read_b32 v195, v195 offset:928
	v_lshl_add_u32 v196, v223, 2, v142
	ds_read_b32 v196, v196 offset:928
	s_waitcnt lgkmcnt(0)
	s_and_saveexec_b64 s[48:49], s[50:51]
	s_cbranch_execz .LBB0_519
	s_nop 2
	v_fmamk_f32 v115, v162, 0x413504f3, v96

; __device__ __forceinline__ void partialSM(f32x16& p0, f32x16& p1, float& m_reg, float& mn, float& alpha, float C, float thrRaw) {
;   float pmax = p0[0];
; #pragma unroll
;   for (int r = 1; r < 16; ++r) pmax = fmaxf(pmax, p0[r]);
; #pragma unroll
;   for (int r = 0; r < 16; ++r) pmax = fmaxf(pmax, p1[r]);
;   { auto rr = __builtin_amdgcn_permlane32_swap(__float_as_uint(pmax), __float_as_uint(pmax), false, false);
;     pmax = fmaxf(__uint_as_float(rr[0]), __uint_as_float(rr[1])); }
;   if (__builtin_expect(__all(pmax - m_reg <= thrRaw), 1)) { mn = m_reg; alpha = 1.f; }
;   else { mn = fmaxf(m_reg, pmax); alpha = __builtin_amdgcn_exp2f((m_reg - mn) * C); m_reg = mn; }
;   float mnC = -mn * C;
; #pragma unroll
;   for (int r = 0; r < 16; ++r) p0[r] = fmaf(p0[r], C, mnC);
; #pragma unroll
;   for (int r = 0; r < 16; ++r) p1[r] = fmaf(p1[r], C, mnC);
; #pragma unroll
;   for (int r = 0; r < 16; ++r) p0[r] = __builtin_amdgcn_exp2f(p0[r]);
; }
; __device__ __forceinline__ void finishSM(f32x16& p0, f32x16& p1, float alpha, float& l_reg, bf16x8& pa0, bf16x8& pa1, bf16x8& pa2, bf16x8& pa3) {
; #pragma unroll
;   for (int r = 0; r < 16; ++r) p1[r] = __builtin_amdgcn_exp2f(p1[r]);
;   float ps = 0;
; #pragma unroll
;   for (int r = 0; r < 16; ++r) ps += p0[r];
; #pragma unroll
;   for (int r = 0; r < 16; ++r) ps += p1[r];
;   { auto rr = __builtin_amdgcn_permlane32_swap(__float_as_uint(ps), __float_as_uint(ps), false, false);
;     ps = __uint_as_float(rr[0]) + __uint_as_float(rr[1]); }
;   l_reg = l_reg * alpha + ps;
;     ...
;   PK4(p0, 0, pa0); PK4(p0, 8, pa1); PK4(p1, 0, pa2); PK4(p1, 8, pa3);
;     ...
; }
; template <int D0> __device__ __forceinline__ void pv_one(f32x16& od, int vb, bf16x8 pa0, bf16x8 pa1, bf16x8 pa2, bf16x8 pa3) {
;   const s16x4 l0 = tr_read<v_rd_off(D0, 0, 0)>(vb), h0 = tr_read<v_rd_off(D0, 0, 1)>(vb), l1 = tr_read<v_rd_off(D0, 1, 0)>(vb), h1 = tr_read<v_rd_off(D0, 1, 1)>(vb);
;   const s16x4 l2 = tr_read<v_rd_off(D0, 2, 0)>(vb), h2 = tr_read<v_rd_off(D0, 2, 1)>(vb), l3 = tr_read<v_rd_off(D0, 3, 0)>(vb), h3 = tr_read<v_rd_off(D0, 3, 1)>(vb);
;   asm volatile("s_waitcnt lgkmcnt(0)" ::: "memory"); SBAR();
;     ...
;   od = __builtin_amdgcn_mfma_f32_32x32x16_bf16(pa0, PK(l0, h0), od, 0, 0, 0);
;   od = __builtin_amdgcn_mfma_f32_32x32x16_bf16(pa1, PK(l1, h1), od, 0, 0, 0);
;   od = __builtin_amdgcn_mfma_f32_32x32x16_bf16(pa2, PK(l2, h2), od, 0, 0, 0);
.LBB0_581:
	s_or_b64 exec, exec, s[36:37]
	v_add_f32_e32 v110, 0, v121
	v_add_f32_e32 v110, v123, v110
	v_add_f32_e32 v110, v12, v110
	v_add_f32_e32 v110, v122, v110
	v_add_f32_e32 v110, v10, v110
	v_add_f32_e32 v110, v13, v110
	v_add_f32_e32 v110, v9, v110
	v_add_f32_e32 v110, v11, v110
	v_add_f32_e32 v110, v6, v110
	v_add_f32_e32 v110, v8, v110
	v_add_f32_e32 v110, v4, v110
	v_add_f32_e32 v110, v7, v110
	v_exp_f32_e32 v80, v124
	v_add_f32_e32 v110, v2, v110
	v_exp_f32_e32 v81, v125
	v_add_f32_e32 v110, v5, v110
	v_exp_f32_e32 v82, v126
	v_add_f32_e32 v110, v0, v110
	v_exp_f32_e32 v83, v130
	v_add_f32_e32 v110, v3, v110
	v_exp_f32_e32 v95, v131
	v_add_f32_e32 v110, v80, v110
	v_exp_f32_e32 v142, v132
	v_add_f32_e32 v110, v81, v110
	v_exp_f32_e32 v143, v133
	v_add_f32_e32 v110, v82, v110
	v_exp_f32_e32 v144, v134
	v_add_f32_e32 v110, v83, v110
	v_exp_f32_e32 v145, v135
	v_add_f32_e32 v110, v95, v110
	v_exp_f32_e32 v164, v136
	v_add_f32_e32 v110, v142, v110
	v_exp_f32_e32 v165, v137
	v_add_f32_e32 v110, v143, v110
	v_exp_f32_e32 v166, v138
	v_add_f32_e32 v110, v144, v110
	v_exp_f32_e32 v167, v139
	v_add_f32_e32 v110, v145, v110
	v_exp_f32_e32 v140, v140
	v_add_f32_e32 v110, v164, v110
	v_exp_f32_e32 v141, v141
	v_add_f32_e32 v110, v165, v110
	v_exp_f32_e32 v172, v127
	v_add_f32_e32 v110, v166, v110
	v_add_f32_e32 v110, v167, v110
	v_add_f32_e32 v110, v140, v110
	v_add_f32_e32 v110, v141, v110
	v_add_f32_e32 v110, v172, v110
	v_mov_b32_e32 v111, v110
	s_nop 1
	v_permlane32_swap_b32_e32 v110, v111
	v_cvt_pk_bf16_f32 v124, v121, v123
	v_cvt_pk_bf16_f32 v125, v12, v122
	v_cvt_pk_bf16_f32 v126, v10, v13
	v_cvt_pk_bf16_f32 v127, v9, v11
	v_cvt_pk_bf16_f32 v130, v6, v8
	v_cvt_pk_bf16_f32 v131, v4, v7
	v_cvt_pk_bf16_f32 v132, v2, v5
	v_cvt_pk_bf16_f32 v133, v0, v3
	v_cvt_pk_bf16_f32 v134, v80, v81
	v_cvt_pk_bf16_f32 v135, v82, v83
	v_cvt_pk_bf16_f32 v136, v95, v142
	v_cvt_pk_bf16_f32 v137, v143, v144
	v_cvt_pk_bf16_f32 v138, v145, v164
	v_cvt_pk_bf16_f32 v139, v165, v166
	v_cvt_pk_bf16_f32 v140, v167, v140
	v_cvt_pk_bf16_f32 v141, v141, v172
	s_nop 0
	v_permlane32_swap_b32_e32 v124, v126
	v_permlane32_swap_b32_e32 v125, v127
	v_permlane32_swap_b32_e32 v130, v132
	v_permlane32_swap_b32_e32 v131, v133
	v_permlane32_swap_b32_e32 v134, v136
	v_permlane32_swap_b32_e32 v135, v137
	v_permlane32_swap_b32_e32 v138, v140
	v_permlane32_swap_b32_e32 v139, v141
	s_mov_b32 s36, 0xa0000
	v_add_co_u32_e32 v6, vcc, s36, v128
	s_mov_b32 s36, 0xf0000
	s_nop 0
	v_addc_co_u32_e32 v7, vcc, 0, v129, vcc
	v_add_co_u32_e32 v10, vcc, s36, v128
	s_nop 1
	v_addc_co_u32_e32 v11, vcc, 0, v129, vcc
	global_load_dwordx4 v[2:5], v[6:7], off offset:1024
	s_nop 0
	global_load_dwordx4 v[6:9], v[6:7], off
	s_nop 0
	global_load_dwordx4 v[80:83], v[10:11], off offset:1024
	s_nop 0
	global_load_dwordx4 v[10:13], v[10:11], off
	ds_read_b64_tr_b16 v[142:143], v149 offset:0
	ds_read_b64_tr_b16 v[144:145], v149 offset:0x800
	ds_read_b64_tr_b16 v[164:165], v149 offset:0x1000
	ds_read_b64_tr_b16 v[166:167], v149 offset:0x1800
	ds_read_b64_tr_b16 v[244:245], v149 offset:0x2000
	ds_read_b64_tr_b16 v[246:247], v149 offset:0x2800
	ds_read_b64_tr_b16 v[172:173], v149 offset:0x3000
	ds_read_b64_tr_b16 v[174:175], v149 offset:0x3800
	s_waitcnt lgkmcnt(0)
	s_nop 0
	v_mfma_f32_32x32x16_bf16 v[32:47], v[124:127], v[142:145], v[32:47]
	ds_read_b64_tr_b16 v[142:143], v149 offset:0x200
	ds_read_b64_tr_b16 v[144:145], v149 offset:0xa00
	v_mfma_f32_32x32x16_bf16 v[32:47], v[130:133], v[164:167], v[32:47]
	ds_read_b64_tr_b16 v[164:165], v149 offset:0x1200
	ds_read_b64_tr_b16 v[166:167], v149 offset:0x1a00
	v_mfma_f32_32x32x16_bf16 v[32:47], v[134:137], v[244:247], v[32:47]
	v_mfma_f32_32x32x16_bf16 v[32:47], v[138:141], v[172:175], v[32:47]
	ds_read_b64_tr_b16 v[172:173], v149 offset:0x2200
	ds_read_b64_tr_b16 v[174:175], v149 offset:0x2a00
	ds_read_b64_tr_b16 v[244:245], v149 offset:0x3200
	ds_read_b64_tr_b16 v[246:247], v149 offset:0x3a00
	s_waitcnt lgkmcnt(0)
	v_mfma_f32_32x32x16_bf16 v[64:79], v[124:127], v[142:145], v[64:79]
	ds_read_b64_tr_b16 v[142:143], v149 offset:0x400
	ds_read_b64_tr_b16 v[144:145], v149 offset:0xc00
	v_mfma_f32_32x32x16_bf16 v[64:79], v[130:133], v[164:167], v[64:79]
	ds_read_b64_tr_b16 v[164:165], v149 offset:0x1400
	ds_read_b64_tr_b16 v[166:167], v149 offset:0x1c00
	v_mfma_f32_32x32x16_bf16 v[64:79], v[134:137], v[172:175], v[64:79]
	ds_read_b64_tr_b16 v[172:173], v149 offset:0x2400
	ds_read_b64_tr_b16 v[174:175], v149 offset:0x2c00
	v_mfma_f32_32x32x16_bf16 v[64:79], v[138:141], v[244:247], v[64:79]
	ds_read_b64_tr_b16 v[244:245], v149 offset:0x3400
	ds_read_b64_tr_b16 v[246:247], v149 offset:0x3c00
	s_waitcnt lgkmcnt(0)
	v_mfma_f32_32x32x16_bf16 v[16:31], v[124:127], v[142:145], v[16:31]
	ds_read_b64_tr_b16 v[142:143], v149 offset:0x600
	ds_read_b64_tr_b16 v[144:145], v149 offset:0xe00
	v_mfma_f32_32x32x16_bf16 v[16:31], v[130:133], v[164:167], v[16:31]
	ds_read_b64_tr_b16 v[164:165], v149 offset:0x1600
	ds_read_b64_tr_b16 v[166:167], v149 offset:0x1e00
	v_mfma_f32_32x32x16_bf16 v[16:31], v[134:137], v[172:175], v[16:31]
	ds_read_b64_tr_b16 v[172:173], v149 offset:0x2600
	ds_read_b64_tr_b16 v[174:175], v149 offset:0x2e00
	v_mfma_f32_32x32x16_bf16 v[16:31], v[138:141], v[244:247], v[16:31]
	ds_read_b64_tr_b16 v[244:245], v149 offset:0x3600
	ds_read_b64_tr_b16 v[246:247], v149 offset:0x3e00
	s_waitcnt lgkmcnt(0)
	v_mfma_f32_32x32x16_bf16 v[48:63], v[124:127], v[142:145], v[48:63]
	v_max_f32_e32 v0, v117, v117
	v_max_f32_e32 v95, v115, v115
	v_max_f32_e32 v0, v95, v0
	v_max3_f32 v0, v0, v118, v119
	v_max3_f32 v0, v0, v120, v100
	v_max3_f32 v0, v0, v101, v102
	v_max3_f32 v0, v0, v103, v104
	v_max3_f32 v0, v0, v105, v106
	v_max3_f32 v0, v0, v107, v108
	v_mfma_f32_32x32x16_bf16 v[48:63], v[130:133], v[164:167], v[48:63]
	v_max3_f32 v0, v0, v109, v94
	v_max3_f32 v0, v0, v14, v15
	v_max3_f32 v0, v0, v96, v97
	v_max3_f32 v0, v0, v98, v99
	v_max3_f32 v0, v0, v84, v85
	v_max3_f32 v0, v0, v86, v87
	v_max3_f32 v0, v0, v88, v89
	v_max3_f32 v0, v0, v90, v91
	v_mfma_f32_32x32x16_bf16 v[48:63], v[134:137], v[172:175], v[48:63]
	v_max3_f32 v0, v0, v92, v93
	v_mov_b32_e32 v95, v0
	s_nop 1
	v_permlane32_swap_b32_e32 v0, v95
	v_max_f32_e32 v95, v95, v95
	v_max_f32_e32 v0, v0, v0
	v_max_f32_e32 v0, v0, v95
	v_sub_f32_e32 v95, v0, v116
	s_mov_b32 s36, 0x42b504f3
	v_cmp_ge_f32_e32 vcc, s36, v95
	v_max_f32_e32 v95, v116, v116
	v_max_f32_e32 v95, v95, v0
	v_mfma_f32_32x32x16_bf16 v[48:63], v[138:141], v[244:247], v[48:63]
	v_sub_f32_e32 v0, v116, v95
	v_mul_f32_e32 v0, 0x3e0293ee, v0
	v_exp_f32_e32 v0, v0
	s_cmp_eq_u64 vcc, exec
	s_cselect_b64 s[36:37], -1, 0
	s_waitcnt vmcnt(0)
	v_cndmask_b32_e64 v0, v0, 1.0, s[36:37]
	v_cmp_gt_f32_e32 vcc, 1.0, v0
	v_mov_b64_e32 v[168:169], v[2:3]
	v_mov_b64_e32 v[170:171], v[4:5]
	v_mov_b64_e32 v[194:195], v[80:81]
	v_mov_b64_e32 v[196:197], v[82:83]
	ds_write_b128 v156, v[6:9] offset:49152
	ds_write_b128 v157, v[10:13] offset:49152
	s_cbranch_vccz .LBB0_585
; #define SBAR() __builtin_amdgcn_sched_barrier(0)
; #define SLOAD(i, k0) do { sr_[i].vs0 = *reinterpret_cast<const bf16x8*>(&Vh[(long)((k0) + sr) * LDP + sc]); sr_[i].vs1 = *reinterpret_cast<const bf16x8*>(&Vh[(long)((k0) + 32 + sr) * LDP + sc]); \
;     sr_[i].ks0 = *reinterpret_cast<const bf16x8*>(&Kh[(long)((k0) + ksr) * LDP + ksc]); if (DK == 128) sr_[i].ks1 = *reinterpret_cast<const bf16x8*>(&Kh[(long)((k0) + 32 + ksr) * LDP + ksc]); } while (0)
; #define SWAIT() do { if (SD == 1) asm volatile("s_waitcnt vmcnt(0)" ::: "memory"); else if (DK == 128) asm volatile("s_waitcnt vmcnt(4)" ::: "memory"); else asm volatile("s_waitcnt vmcnt(3)" ::: "memory"); } while (0)
; #define RESC(a) do { if (__any((a) < 1.f)) { if (hi == 0) al_l[r32] = (a); asm volatile("s_waitcnt lgkmcnt(0)" ::: "memory"); \
;     _Pragma("unroll") for (int d = 0; d < 4; ++d) _Pragma("unroll") for (int r = 0; r < 16; ++r) o[d][r] *= al_l[crow(r, hi)]; } } while (0)
; #define HOOK(P0, P1, j) do { if (NA) na_hook(P0, P1, krow0 + (j), q_row, q_col, win_r, win_c, rpb, inv_scale, hi); } while (0)
; __device__ __forceinline__ void partialSM(f32x16& p0, f32x16& p1, float& m_reg, float& mn, float& alpha, float C, float thrRaw) {
;     ...
;     pmax = fmaxf(__uint_as_float(rr[0]), __uint_as_float(rr[1])); }
;   if (__builtin_expect(__all(pmax - m_reg <= thrRaw), 1)) { mn = m_reg; alpha = 1.f; }
;   else { mn = fmaxf(m_reg, pmax); alpha = __builtin_amdgcn_exp2f((m_reg - mn) * C); m_reg = mn; }
;   float mnC = -mn * C;
; #pragma unroll
;   for (int r = 0; r < 16; ++r) p0[r] = fmaf(p0[r], C, mnC);
; #pragma unroll
;   for (int r = 0; r < 16; ++r) p1[r] = fmaf(p1[r], C, mnC);
; #pragma unroll
;   for (int r = 0; r < 16; ++r) p0[r] = __builtin_amdgcn_exp2f(p0[r]);
; template <int DK, bool NA, bool QL, int SD> ...
;     ...
;     SBAR(); qkt<DK, QL>(pA0, pA1, K_lds, qr, ql, r32, hi); HOOK(pA0, pA1, j + 1);
;     finishSM(pB0, pB1, alB, l_reg, pa0, pa1, pa2, pa3); SBAR();
;     if (SD == 1 || j + 3 < NT) SLOAD(SE, (j + 1 + SD) * KVBLK); SBAR();
;     pv_d0(o, vb0 + (int)SHM_V, pa0, pa1, pa2, pa3); partialSM(pA0, pA1, m_reg, mnA, alA, C, thrRaw);
;     __syncthreads(); SWAIT(); SWRITE(1, SO);
;     RESC(alA); __syncthreads();
;   }
	s_mov_b64 s[48:49], exec
	v_readlane_b32 s50, v255, 58
	v_readlane_b32 s51, v255, 59
	s_and_b64 s[50:51], s[48:49], s[50:51]
	s_mov_b64 exec, s[50:51]
	ds_write_b32 v148, v0 offset:128
	s_or_b64 exec, exec, s[48:49]
	s_waitcnt lgkmcnt(0)
	ds_read_b128 v[2:5], v146 offset:128
	ds_read_b128 v[6:9], v146 offset:160
	ds_read_b128 v[10:13], v146 offset:192
	ds_read_b128 v[80:83], v146 offset:224
	s_waitcnt lgkmcnt(3)
	v_pk_mul_f32 v[64:65], v[2:3], v[64:65]
	v_pk_mul_f32 v[66:67], v[66:67], v[4:5]
	s_waitcnt lgkmcnt(2)
	v_pk_mul_f32 v[68:69], v[68:69], v[6:7]
	v_pk_mul_f32 v[70:71], v[70:71], v[8:9]
	s_waitcnt lgkmcnt(1)
	v_pk_mul_f32 v[72:73], v[72:73], v[10:11]
	v_pk_mul_f32 v[74:75], v[74:75], v[12:13]
	s_waitcnt lgkmcnt(0)
	v_pk_mul_f32 v[76:77], v[76:77], v[80:81]
	v_pk_mul_f32 v[46:47], v[46:47], v[82:83]
	v_pk_mul_f32 v[42:43], v[42:43], v[12:13]
	v_pk_mul_f32 v[38:39], v[38:39], v[8:9]
	v_pk_mul_f32 v[34:35], v[34:35], v[4:5]
	v_pk_mul_f32 v[44:45], v[44:45], v[80:81]
	v_pk_mul_f32 v[40:41], v[40:41], v[10:11]
	v_pk_mul_f32 v[36:37], v[36:37], v[6:7]
	v_pk_mul_f32 v[32:33], v[32:33], v[2:3]
	v_pk_mul_f32 v[78:79], v[78:79], v[82:83]
	v_pk_mul_f32 v[48:49], v[2:3], v[48:49]
	v_pk_mul_f32 v[50:51], v[50:51], v[4:5]
	v_pk_mul_f32 v[52:53], v[52:53], v[6:7]
	v_pk_mul_f32 v[54:55], v[54:55], v[8:9]
	v_pk_mul_f32 v[56:57], v[56:57], v[10:11]
	v_pk_mul_f32 v[58:59], v[58:59], v[12:13]
	v_pk_mul_f32 v[60:61], v[60:61], v[80:81]
	v_pk_mul_f32 v[30:31], v[30:31], v[82:83]
	v_pk_mul_f32 v[26:27], v[26:27], v[12:13]
	v_pk_mul_f32 v[22:23], v[22:23], v[8:9]
	v_pk_mul_f32 v[18:19], v[18:19], v[4:5]
	v_pk_mul_f32 v[28:29], v[28:29], v[80:81]
	v_pk_mul_f32 v[24:25], v[24:25], v[10:11]
	v_pk_mul_f32 v[20:21], v[20:21], v[6:7]
	v_pk_mul_f32 v[16:17], v[16:17], v[2:3]
	v_pk_mul_f32 v[62:63], v[62:63], v[82:83]
.LBB0_585:
	v_cndmask_b32_e64 v237, v95, v116, s[36:37]
	v_mul_f32_e32 v2, 0xbe0293ee, v237
	v_fmamk_f32 v11, v103, 0x3e0293ee, v2
	v_mov_b32_e32 v103, v2
	v_fmamk_f32 v3, v115, 0x3e0293ee, v2
	v_fmamk_f32 v4, v117, 0x3e0293ee, v2
	v_fmamk_f32 v5, v118, 0x3e0293ee, v2
	v_fmamk_f32 v6, v119, 0x3e0293ee, v2
	v_fmamk_f32 v7, v120, 0x3e0293ee, v2
	v_fmamk_f32 v8, v100, 0x3e0293ee, v2
	v_fmamk_f32 v9, v101, 0x3e0293ee, v2
	v_fmamk_f32 v10, v102, 0x3e0293ee, v2
	v_fmamk_f32 v12, v104, 0x3e0293ee, v2
	v_fmamk_f32 v13, v105, 0x3e0293ee, v2
	v_fmamk_f32 v83, v106, 0x3e0293ee, v2
	v_fmamk_f32 v100, v107, 0x3e0293ee, v2
	v_fmamk_f32 v101, v108, 0x3e0293ee, v2
	v_fmamk_f32 v102, v109, 0x3e0293ee, v2
	v_fmac_f32_e32 v103, 0x3e0293ee, v94
	s_mov_b32 s36, 0x3e0293ee
	v_pk_fma_f32 v[138:139], v[84:85], s[36:37], v[2:3] op_sel_hi:[1,0,0]
	v_pk_fma_f32 v[136:137], v[86:87], s[36:37], v[2:3] op_sel_hi:[1,0,0]
	v_pk_fma_f32 v[134:135], v[88:89], s[36:37], v[2:3] op_sel_hi:[1,0,0]
	v_pk_fma_f32 v[132:133], v[90:91], s[36:37], v[2:3] op_sel_hi:[1,0,0]
	v_pk_fma_f32 v[130:131], v[92:93], s[36:37], v[2:3] op_sel_hi:[1,0,0]
	v_exp_f32_e32 v94, v3
	v_exp_f32_e32 v95, v4
	v_exp_f32_e32 v92, v5
	v_exp_f32_e32 v93, v6
	v_exp_f32_e32 v88, v7
	v_exp_f32_e32 v89, v8
	v_exp_f32_e32 v90, v9
	v_exp_f32_e32 v91, v10
	v_exp_f32_e32 v80, v11
	v_exp_f32_e32 v81, v12
	v_exp_f32_e32 v82, v13
	v_exp_f32_e32 v83, v83
	v_exp_f32_e32 v84, v100
	v_exp_f32_e32 v85, v101
	v_exp_f32_e32 v86, v102
	v_exp_f32_e32 v87, v103
	v_pk_fma_f32 v[144:145], v[14:15], s[36:37], v[2:3] op_sel_hi:[1,0,0]
	v_pk_fma_f32 v[142:143], v[96:97], s[36:37], v[2:3] op_sel_hi:[1,0,0]
	v_pk_fma_f32 v[140:141], v[98:99], s[36:37], v[2:3] op_sel_hi:[1,0,0]
	v_add_f32_e32 v2, v112, v113
	v_fmac_f32_e32 v2, v239, v150
	v_add_f32_e32 v150, v110, v111
	s_add_i32 s33, s33, 2
	s_mov_b64 s[36:37], 0x140000
	v_fmac_f32_e32 v150, v2, v114
	s_cmp_gt_u32 s33, 8
	v_lshl_add_u64 v[128:129], v[128:129], 0, s[36:37]
	s_waitcnt lgkmcnt(0)
	s_barrier
	ds_write_b128 v152, v[168:171] offset:16384
	ds_write_b128 v153, v[194:197] offset:16384
	s_cbranch_scc1 .LBB0_587
	v_mov_b32_e32 v239, v0
	s_branch .LBB0_449
